# tail_proj (recurrent-in phase): 48 of the 64 operand loads in flight instead of 4 serialized rounds of 16
# speedup vs baseline: 1.0022x; 1.0022x over previous
.LBB0_195:
	s_andn2_b64 vcc, exec, s[4:5]
	s_cbranch_vccnz .LBB0_197
	s_waitcnt vmcnt(0)
	v_mov_b32_e32 v4, v192
	s_load_dwordx4 s[4:7], s[8:9], 0xb8
	v_readlane_b32 s8, v253, 32
	v_ashrrev_i32_e32 v0, 2, v4
	v_bfi_b32 v0, -16, v0, v4
	v_add_u32_e32 v68, 0x4000, v0
	v_ashrrev_i32_e32 v69, 31, v68
	v_readlane_b32 s9, v253, 33
	s_waitcnt vmcnt(0)
	v_bfe_u32 v64, v4, 4, 2
	v_lshlrev_b64 v[0:1], 11, v[68:69]
	s_lshl_b64 s[8:9], s[8:9], 1
	s_waitcnt lgkmcnt(0)
	v_lshl_add_u64 v[0:1], s[4:5], 0, v[0:1]
	v_lshlrev_b32_e32 v2, 4, v64
	v_mov_b32_e32 v3, v173
	s_add_u32 s8, s6, s8
	v_lshl_add_u64 v[0:1], v[0:1], 0, v[2:3]
	s_mov_b64 s[4:5], 0x8000
	s_addc_u32 s9, s7, s9
	v_lshl_add_u64 v[70:71], v[0:1], 0, s[4:5]
	s_lshl_b32 s4, s0, 4
	v_and_or_b32 v4, v4, 15, s4
	v_ashrrev_i32_e32 v5, 31, v4
	v_lshlrev_b64 v[4:5], 11, v[4:5]
	s_mov_b32 s0, 0x8000
	v_lshl_add_u64 v[4:5], s[8:9], 0, v[4:5]
	v_add_co_u32_e32 v0, vcc, s0, v0
	v_lshl_add_u64 v[4:5], v[4:5], 0, v[2:3]
	s_mov_b64 s[8:9], 0x1000
	v_addc_co_u32_e32 v1, vcc, 0, v1, vcc
	s_movk_i32 s0, 0x1000
	v_lshl_add_u64 v[72:73], v[4:5], 0, s[8:9]
	v_add_co_u32_e32 v4, vcc, s0, v4
	v_addc_co_u32_e32 v5, vcc, 0, v5, vcc
	v_lshlrev_b32_e32 v172, 3, v64
	global_load_dwordx4 v[4:7], v[70:71], off
	global_load_dwordx4 v[8:11], v[72:73], off
	global_load_dwordx4 v[12:15], v[70:71], off offset:64
	global_load_dwordx4 v[16:19], v[72:73], off offset:64
	global_load_dwordx4 v[20:23], v[70:71], off offset:128
	global_load_dwordx4 v[24:27], v[72:73], off offset:128
	global_load_dwordx4 v[28:31], v[70:71], off offset:192
	global_load_dwordx4 v[32:35], v[72:73], off offset:192
	global_load_dwordx4 v[36:39], v[70:71], off offset:256
	global_load_dwordx4 v[40:43], v[72:73], off offset:256
	global_load_dwordx4 v[44:47], v[70:71], off offset:320
	global_load_dwordx4 v[48:51], v[72:73], off offset:320
	global_load_dwordx4 v[52:55], v[70:71], off offset:384
	global_load_dwordx4 v[56:59], v[72:73], off offset:384
	global_load_dwordx4 v[60:63], v[70:71], off offset:448
	global_load_dwordx4 v[64:67], v[72:73], off offset:448
	global_load_dwordx4 v[76:79], v[70:71], off offset:512
	global_load_dwordx4 v[80:83], v[72:73], off offset:512
	global_load_dwordx4 v[84:87], v[70:71], off offset:576
	global_load_dwordx4 v[88:91], v[72:73], off offset:576
	global_load_dwordx4 v[92:95], v[70:71], off offset:640
	global_load_dwordx4 v[96:99], v[72:73], off offset:640
	global_load_dwordx4 v[100:103], v[70:71], off offset:704
	global_load_dwordx4 v[104:107], v[72:73], off offset:704
	global_load_dwordx4 v[108:111], v[70:71], off offset:768
	global_load_dwordx4 v[112:115], v[72:73], off offset:768
	global_load_dwordx4 v[116:119], v[70:71], off offset:832
	global_load_dwordx4 v[120:123], v[72:73], off offset:832
	global_load_dwordx4 v[124:127], v[70:71], off offset:896
	global_load_dwordx4 v[128:131], v[72:73], off offset:896
	global_load_dwordx4 v[132:135], v[70:71], off offset:960
	global_load_dwordx4 v[136:139], v[72:73], off offset:960
	global_load_dwordx4 v[140:143], v[70:71], off offset:1024
	global_load_dwordx4 v[144:147], v[72:73], off offset:1024
	global_load_dwordx4 v[148:151], v[70:71], off offset:1088
	global_load_dwordx4 v[152:155], v[72:73], off offset:1088
	global_load_dwordx4 v[156:159], v[70:71], off offset:1152
	global_load_dwordx4 v[160:163], v[72:73], off offset:1152
	global_load_dwordx4 v[164:167], v[70:71], off offset:1216
	global_load_dwordx4 v[168:171], v[72:73], off offset:1216
	global_load_dwordx4 v[204:207], v[70:71], off offset:1280
	global_load_dwordx4 v[208:211], v[72:73], off offset:1280
	global_load_dwordx4 v[212:215], v[70:71], off offset:1344
	global_load_dwordx4 v[216:219], v[72:73], off offset:1344
	global_load_dwordx4 v[220:223], v[70:71], off offset:1408
	global_load_dwordx4 v[224:227], v[72:73], off offset:1408
	global_load_dwordx4 v[228:231], v[70:71], off offset:1472
	global_load_dwordx4 v[232:235], v[72:73], off offset:1472
	s_waitcnt vmcnt(46)
	v_mfma_f32_16x16x32_bf16 v[0:3], v[8:11], v[4:7], 0
	s_waitcnt vmcnt(44)
	v_mfma_f32_16x16x32_bf16 v[0:3], v[16:19], v[12:15], v[0:3]
	s_waitcnt vmcnt(42)
	v_mfma_f32_16x16x32_bf16 v[0:3], v[24:27], v[20:23], v[0:3]
	s_waitcnt vmcnt(40)
	v_mfma_f32_16x16x32_bf16 v[0:3], v[32:35], v[28:31], v[0:3]
	s_waitcnt vmcnt(38)
	v_mfma_f32_16x16x32_bf16 v[0:3], v[40:43], v[36:39], v[0:3]
	s_waitcnt vmcnt(36)
	v_mfma_f32_16x16x32_bf16 v[0:3], v[48:51], v[44:47], v[0:3]
	s_waitcnt vmcnt(34)
	v_mfma_f32_16x16x32_bf16 v[0:3], v[56:59], v[52:55], v[0:3]
	s_waitcnt vmcnt(32)
	v_mfma_f32_16x16x32_bf16 v[0:3], v[64:67], v[60:63], v[0:3]
	global_load_dwordx4 v[4:7], v[70:71], off offset:1536
	global_load_dwordx4 v[8:11], v[72:73], off offset:1536
	global_load_dwordx4 v[12:15], v[70:71], off offset:1600
	global_load_dwordx4 v[16:19], v[72:73], off offset:1600
	global_load_dwordx4 v[20:23], v[70:71], off offset:1664
	global_load_dwordx4 v[24:27], v[72:73], off offset:1664
	global_load_dwordx4 v[28:31], v[70:71], off offset:1728
	global_load_dwordx4 v[32:35], v[72:73], off offset:1728
	global_load_dwordx4 v[36:39], v[70:71], off offset:1792
	global_load_dwordx4 v[40:43], v[72:73], off offset:1792
	global_load_dwordx4 v[44:47], v[70:71], off offset:1856
	global_load_dwordx4 v[48:51], v[72:73], off offset:1856
	global_load_dwordx4 v[52:55], v[70:71], off offset:1920
	global_load_dwordx4 v[56:59], v[72:73], off offset:1920
	global_load_dwordx4 v[60:63], v[70:71], off offset:1984
	global_load_dwordx4 v[64:67], v[72:73], off offset:1984
	s_waitcnt vmcnt(46)
	v_mfma_f32_16x16x32_bf16 v[0:3], v[80:83], v[76:79], v[0:3]
	s_waitcnt vmcnt(44)
	v_mfma_f32_16x16x32_bf16 v[0:3], v[88:91], v[84:87], v[0:3]
	s_waitcnt vmcnt(42)
	v_mfma_f32_16x16x32_bf16 v[0:3], v[96:99], v[92:95], v[0:3]
	s_waitcnt vmcnt(40)
	v_mfma_f32_16x16x32_bf16 v[0:3], v[104:107], v[100:103], v[0:3]
	s_waitcnt vmcnt(38)
	v_mfma_f32_16x16x32_bf16 v[0:3], v[112:115], v[108:111], v[0:3]
	s_waitcnt vmcnt(36)
	v_mfma_f32_16x16x32_bf16 v[0:3], v[120:123], v[116:119], v[0:3]
	s_waitcnt vmcnt(34)
	v_mfma_f32_16x16x32_bf16 v[0:3], v[128:131], v[124:127], v[0:3]
	s_waitcnt vmcnt(32)
	v_mfma_f32_16x16x32_bf16 v[0:3], v[136:139], v[132:135], v[0:3]
	s_waitcnt vmcnt(30)
	v_mfma_f32_16x16x32_bf16 v[0:3], v[144:147], v[140:143], v[0:3]
	s_waitcnt vmcnt(28)
	v_mfma_f32_16x16x32_bf16 v[0:3], v[152:155], v[148:151], v[0:3]
	s_waitcnt vmcnt(26)
	v_mfma_f32_16x16x32_bf16 v[0:3], v[160:163], v[156:159], v[0:3]
	s_waitcnt vmcnt(24)
	v_mfma_f32_16x16x32_bf16 v[0:3], v[168:171], v[164:167], v[0:3]
	s_waitcnt vmcnt(22)
	v_mfma_f32_16x16x32_bf16 v[0:3], v[208:211], v[204:207], v[0:3]
	s_waitcnt vmcnt(20)
	v_mfma_f32_16x16x32_bf16 v[0:3], v[216:219], v[212:215], v[0:3]
	s_waitcnt vmcnt(18)
	v_mfma_f32_16x16x32_bf16 v[0:3], v[224:227], v[220:223], v[0:3]
	s_waitcnt vmcnt(16)
	v_mfma_f32_16x16x32_bf16 v[0:3], v[232:235], v[228:231], v[0:3]
	s_waitcnt vmcnt(14)
	v_mfma_f32_16x16x32_bf16 v[0:3], v[8:11], v[4:7], v[0:3]
	s_waitcnt vmcnt(12)
	v_mfma_f32_16x16x32_bf16 v[0:3], v[16:19], v[12:15], v[0:3]
	s_waitcnt vmcnt(10)
	v_mfma_f32_16x16x32_bf16 v[0:3], v[24:27], v[20:23], v[0:3]
	s_waitcnt vmcnt(8)
	v_mfma_f32_16x16x32_bf16 v[0:3], v[32:35], v[28:31], v[0:3]
	s_waitcnt vmcnt(6)
	v_mfma_f32_16x16x32_bf16 v[0:3], v[40:43], v[36:39], v[0:3]
	s_waitcnt vmcnt(4)
	v_mfma_f32_16x16x32_bf16 v[0:3], v[48:51], v[44:47], v[0:3]
	s_waitcnt vmcnt(2)
	v_mfma_f32_16x16x32_bf16 v[0:3], v[56:59], v[52:55], v[0:3]
	s_waitcnt vmcnt(0)
	v_mfma_f32_16x16x32_bf16 v[0:3], v[64:67], v[60:63], v[0:3]
	s_nop 7
	v_bfe_u32 v4, v0, 16, 1
	v_add3_u32 v0, v0, v4, s96
	v_bfe_u32 v4, v1, 16, 1
	v_lshrrev_b32_e32 v0, 16, v0
	v_add3_u32 v1, v1, v4, s96
	s_mov_b32 s0, 0xffff0000
	v_and_or_b32 v0, v1, s0, v0
	v_bfe_u32 v1, v2, 16, 1
	v_add3_u32 v1, v2, v1, s96
	v_bfe_u32 v2, v3, 16, 1
	v_lshrrev_b32_e32 v1, 16, v1
	v_add3_u32 v2, v3, v2, s96
	v_and_or_b32 v1, v2, s0, v1
	v_mov_b64_e32 v[2:3], s[6:7]
	s_movk_i32 s0, 0x1800
	v_mad_i64_i32 v[2:3], s[6:7], v68, s0, v[2:3]
	s_ashr_i32 s5, s4, 31
	v_lshl_add_u64 v[2:3], s[4:5], 1, v[2:3]
	v_lshl_add_u64 v[2:3], v[2:3], 0, v[172:173]
	v_add_co_u32_e32 v2, vcc, 0x8f29000, v2
	s_nop 1
	v_addc_co_u32_e32 v3, vcc, 0, v3, vcc
	global_store_dwordx2 v[2:3], v[0:1], off
